# grid barrier with one hop less (leader invalidates after its write-back, last leader releases every XCD), stacked on v58
# speedup vs baseline: 1.0006x; 1.0006x over previous
.LBB0_170:
	s_andn2_saveexec_b64 s[2:3], s[8:9]
	s_cbranch_execz .LBB0_188
	s_mov_b64 s[8:9], exec
	buffer_wbl2 sc1
	s_waitcnt vmcnt(0) lgkmcnt(0)
	s_waitcnt vmcnt(0)
	buffer_inv sc1
	s_waitcnt vmcnt(0)
	v_mbcnt_lo_u32_b32 v3, s8, 0
	v_mbcnt_hi_u32_b32 v3, s9, v3
	v_cmp_eq_u32_e32 vcc, 0, v3
	s_and_saveexec_b64 s[10:11], vcc
	s_cbranch_execz .LBB0_173
	s_bcnt1_i32_b64 s2, s[8:9]
	v_mov_b32_e32 v4, 0x4000
	v_mov_b32_e32 v5, s2
	global_atomic_add v4, v4, v5, s[70:71] offset:1024 sc0
.LBB0_173:
	s_or_b64 exec, exec, s[10:11]
	v_cvt_f32_u32_e32 v5, v2
	s_waitcnt vmcnt(0)
	v_readfirstlane_b32 s2, v4
	s_add_u32 s10, s70, 0x4500
	s_addc_u32 s11, s71, 0
	v_rcp_iflag_f32_e32 v5, v5
	v_add_u32_e32 v3, s2, v3
	v_add_u32_e32 v6, 1, v3
	s_mov_b64 s[24:25], -1
	v_mul_f32_e32 v4, 0x4f7ffffe, v5
	v_cvt_u32_f32_e32 v4, v4
	v_sub_u32_e32 v5, 0, v2
	v_mul_lo_u32 v5, v5, v4
	v_mul_hi_u32 v5, v4, v5
	v_add_u32_e32 v4, v4, v5
	v_mul_hi_u32 v4, v3, v4
	v_mul_lo_u32 v5, v4, v2
	v_sub_u32_e32 v3, v3, v5
	v_add_u32_e32 v7, 1, v4
	v_cmp_ge_u32_e32 vcc, v3, v2
	v_sub_u32_e32 v5, v3, v2
	s_nop 0
	v_cndmask_b32_e32 v4, v4, v7, vcc
	v_cndmask_b32_e32 v3, v3, v5, vcc
	v_add_u32_e32 v5, 1, v4
	v_cmp_ge_u32_e32 vcc, v3, v2
	s_nop 1
	v_cndmask_b32_e32 v4, v4, v5, vcc
	v_mul_lo_u32 v3, v2, v4
	v_add_u32_e32 v2, v3, v2
	v_cmp_ne_u32_e32 vcc, v6, v2
	v_mov_b64_e32 v[2:3], s[10:11]
	s_nop 0
	s_mov_b64 s[98:99], vcc
	s_and_saveexec_b64 s[8:9], vcc
	s_cbranch_execz .LBB0_185
	v_mov_b32_e32 v2, 0
	global_load_dword v3, v2, s[10:11] sc1
	s_mov_b64 s[28:29], 0
	s_waitcnt vmcnt(0)
	v_cmp_eq_u32_e32 vcc, v3, v4
	s_and_saveexec_b64 s[26:27], vcc
	s_cbranch_execz .LBB0_184
	s_add_u32 s24, s70, 0x1200
	s_addc_u32 s25, s71, 0
	s_mov_b32 s2, 1
	s_branch .LBB0_177

.LBB0_187:
	s_or_b64 exec, exec, s[8:9]
	s_waitcnt vmcnt(0)
	s_and_b64 vcc, exec, s[98:99]
	s_cbranch_vccnz .Lbar3_skip_0
	v_readlane_b32 s100, v254, 26
	v_readlane_b32 s101, v254, 27
	v_mov_b32_e32 v2, 0x2400
	v_mov_b32_e32 v3, 1
	s_nop 4
	global_atomic_add v2, v3, s[100:101]
	global_atomic_add v2, v3, s[100:101] offset:256
	global_atomic_add v2, v3, s[100:101] offset:512
	global_atomic_add v2, v3, s[100:101] offset:768
	global_atomic_add v2, v3, s[100:101] offset:1024
	global_atomic_add v2, v3, s[100:101] offset:1280
	global_atomic_add v2, v3, s[100:101] offset:1536
	global_atomic_add v2, v3, s[100:101] offset:1792
	global_atomic_add v2, v3, s[100:101] offset:2048
	global_atomic_add v2, v3, s[100:101] offset:2304
	global_atomic_add v2, v3, s[100:101] offset:2560
	global_atomic_add v2, v3, s[100:101] offset:2816
	global_atomic_add v2, v3, s[100:101] offset:3072
	global_atomic_add v2, v3, s[100:101] offset:3328
	global_atomic_add v2, v3, s[100:101] offset:3584
	global_atomic_add v2, v3, s[100:101] offset:3840
	s_waitcnt vmcnt(0)
.Lbar3_skip_0:
.LBB0_188:
	s_or_b64 exec, exec, s[4:5]
	s_waitcnt lgkmcnt(0)
	s_barrier

.LBB0_903:
	s_andn2_saveexec_b64 s[2:3], s[10:11]
	s_cbranch_execz .LBB0_921
	s_mov_b64 s[10:11], exec
	buffer_wbl2 sc1
	s_waitcnt vmcnt(0) lgkmcnt(0)
	s_waitcnt vmcnt(0)
	buffer_inv sc1
	s_waitcnt vmcnt(0)
	v_mbcnt_lo_u32_b32 v3, s10, 0
	v_mbcnt_hi_u32_b32 v3, s11, v3
	v_cmp_eq_u32_e32 vcc, 0, v3
	s_and_saveexec_b64 s[12:13], vcc
	s_cbranch_execz .LBB0_906
	s_bcnt1_i32_b64 s2, s[10:11]
	v_mov_b32_e32 v4, 0x4000
	v_mov_b32_e32 v5, s2
	global_atomic_add v4, v4, v5, s[70:71] offset:1024 sc0
.LBB0_906:
	s_or_b64 exec, exec, s[12:13]
	v_cvt_f32_u32_e32 v5, v2
	s_waitcnt vmcnt(0)
	v_readfirstlane_b32 s2, v4
	s_add_u32 s12, s70, 0x4500
	s_addc_u32 s13, s71, 0
	v_rcp_iflag_f32_e32 v5, v5
	v_add_u32_e32 v3, s2, v3
	v_add_u32_e32 v6, 1, v3
	s_mov_b64 s[24:25], -1
	v_mul_f32_e32 v4, 0x4f7ffffe, v5
	v_cvt_u32_f32_e32 v4, v4
	v_sub_u32_e32 v5, 0, v2
	v_mul_lo_u32 v5, v5, v4
	v_mul_hi_u32 v5, v4, v5
	v_add_u32_e32 v4, v4, v5
	v_mul_hi_u32 v4, v3, v4
	v_mul_lo_u32 v5, v4, v2
	v_sub_u32_e32 v3, v3, v5
	v_add_u32_e32 v7, 1, v4
	v_cmp_ge_u32_e32 vcc, v3, v2
	v_sub_u32_e32 v5, v3, v2
	s_nop 0
	v_cndmask_b32_e32 v4, v4, v7, vcc
	v_cndmask_b32_e32 v3, v3, v5, vcc
	v_add_u32_e32 v5, 1, v4
	v_cmp_ge_u32_e32 vcc, v3, v2
	s_nop 1
	v_cndmask_b32_e32 v4, v4, v5, vcc
	v_mul_lo_u32 v3, v2, v4
	v_add_u32_e32 v2, v3, v2
	v_cmp_ne_u32_e32 vcc, v6, v2
	v_mov_b64_e32 v[2:3], s[12:13]
	s_nop 0
	s_mov_b64 s[98:99], vcc
	s_and_saveexec_b64 s[10:11], vcc
	s_cbranch_execz .LBB0_918
	v_mov_b32_e32 v2, 0
	global_load_dword v3, v2, s[12:13] sc1
	s_mov_b64 s[28:29], 0
	s_waitcnt vmcnt(0)
	v_cmp_eq_u32_e32 vcc, v3, v4
	s_and_saveexec_b64 s[26:27], vcc
	s_cbranch_execz .LBB0_917
	s_add_u32 s24, s70, 0x1200
	s_addc_u32 s25, s71, 0
	s_mov_b32 s2, 1
	s_branch .LBB0_910

.LBB0_920:
	s_or_b64 exec, exec, s[10:11]
	s_waitcnt vmcnt(0)
	s_and_b64 vcc, exec, s[98:99]
	s_cbranch_vccnz .Lbar3_skip_3
	v_readlane_b32 s100, v254, 26
	v_readlane_b32 s101, v254, 27
	v_mov_b32_e32 v2, 0x2400
	v_mov_b32_e32 v3, 1
	s_nop 4
	global_atomic_add v2, v3, s[100:101]
	global_atomic_add v2, v3, s[100:101] offset:256
	global_atomic_add v2, v3, s[100:101] offset:512
	global_atomic_add v2, v3, s[100:101] offset:768
	global_atomic_add v2, v3, s[100:101] offset:1024
	global_atomic_add v2, v3, s[100:101] offset:1280
	global_atomic_add v2, v3, s[100:101] offset:1536
	global_atomic_add v2, v3, s[100:101] offset:1792
	global_atomic_add v2, v3, s[100:101] offset:2048
	global_atomic_add v2, v3, s[100:101] offset:2304
	global_atomic_add v2, v3, s[100:101] offset:2560
	global_atomic_add v2, v3, s[100:101] offset:2816
	global_atomic_add v2, v3, s[100:101] offset:3072
	global_atomic_add v2, v3, s[100:101] offset:3328
	global_atomic_add v2, v3, s[100:101] offset:3584
	global_atomic_add v2, v3, s[100:101] offset:3840
	s_waitcnt vmcnt(0)
.Lbar3_skip_3:
.LBB0_921:
	s_or_b64 exec, exec, s[0:1]
	s_waitcnt lgkmcnt(0)
	s_barrier

.LBB0_1269:
	s_or_b64 exec, exec, s[12:13]
	v_cvt_f32_u32_e32 v5, v2
	s_waitcnt vmcnt(0)
	v_readfirstlane_b32 s2, v4
	s_add_u32 s12, s70, 0x4500
	s_addc_u32 s13, s71, 0
	v_rcp_iflag_f32_e32 v5, v5
	v_add_u32_e32 v3, s2, v3
	v_add_u32_e32 v6, 1, v3
	s_mov_b64 s[14:15], -1
	v_mul_f32_e32 v4, 0x4f7ffffe, v5
	v_cvt_u32_f32_e32 v4, v4
	v_sub_u32_e32 v5, 0, v2
	v_mul_lo_u32 v5, v5, v4
	v_mul_hi_u32 v5, v4, v5
	v_add_u32_e32 v4, v4, v5
	v_mul_hi_u32 v4, v3, v4
	v_mul_lo_u32 v5, v4, v2
	v_sub_u32_e32 v3, v3, v5
	v_add_u32_e32 v7, 1, v4
	v_cmp_ge_u32_e32 vcc, v3, v2
	v_sub_u32_e32 v5, v3, v2
	s_nop 0
	v_cndmask_b32_e32 v4, v4, v7, vcc
	v_cndmask_b32_e32 v3, v3, v5, vcc
	v_add_u32_e32 v5, 1, v4
	v_cmp_ge_u32_e32 vcc, v3, v2
	s_nop 1
	v_cndmask_b32_e32 v4, v4, v5, vcc
	v_mul_lo_u32 v3, v2, v4
	v_add_u32_e32 v2, v3, v2
	v_cmp_ne_u32_e32 vcc, v6, v2
	v_mov_b64_e32 v[2:3], s[12:13]
	s_nop 0
	s_mov_b64 s[98:99], vcc
	s_and_saveexec_b64 s[10:11], vcc
	s_cbranch_execz .LBB0_1281
	v_mov_b32_e32 v2, 0
	global_load_dword v3, v2, s[12:13] sc1
	s_mov_b64 s[24:25], 0
	s_waitcnt vmcnt(0)
	v_cmp_eq_u32_e32 vcc, v3, v4
	s_and_saveexec_b64 s[16:17], vcc
	s_cbranch_execz .LBB0_1280
	s_add_u32 s14, s70, 0x1200
	s_addc_u32 s15, s71, 0
	s_mov_b32 s2, 1
	s_branch .LBB0_1273

.Lbar3_skip_4:
.LBB0_1284:
	s_or_b64 exec, exec, s[6:7]
	s_waitcnt lgkmcnt(0)
	s_barrier

.LBB0_1394:
	s_or_b64 exec, exec, s[10:11]
	v_cvt_f32_u32_e32 v5, v2
	s_waitcnt vmcnt(0)
	v_readfirstlane_b32 s2, v4
	s_add_u32 s10, s70, 0x4500
	s_addc_u32 s11, s71, 0
	v_rcp_iflag_f32_e32 v5, v5
	v_add_u32_e32 v3, s2, v3
	v_add_u32_e32 v6, 1, v3
	s_mov_b64 s[12:13], -1
	v_mul_f32_e32 v4, 0x4f7ffffe, v5
	v_cvt_u32_f32_e32 v4, v4
	v_sub_u32_e32 v5, 0, v2
	v_mul_lo_u32 v5, v5, v4
	v_mul_hi_u32 v5, v4, v5
	v_add_u32_e32 v4, v4, v5
	v_mul_hi_u32 v4, v3, v4
	v_mul_lo_u32 v5, v4, v2
	v_sub_u32_e32 v3, v3, v5
	v_add_u32_e32 v7, 1, v4
	v_cmp_ge_u32_e32 vcc, v3, v2
	v_sub_u32_e32 v5, v3, v2
	s_nop 0
	v_cndmask_b32_e32 v4, v4, v7, vcc
	v_cndmask_b32_e32 v3, v3, v5, vcc
	v_add_u32_e32 v5, 1, v4
	v_cmp_ge_u32_e32 vcc, v3, v2
	s_nop 1
	v_cndmask_b32_e32 v4, v4, v5, vcc
	v_mul_lo_u32 v3, v2, v4
	v_add_u32_e32 v2, v3, v2
	v_cmp_ne_u32_e32 vcc, v6, v2
	v_mov_b64_e32 v[2:3], s[10:11]
	s_nop 0
	s_mov_b64 s[98:99], vcc
	s_and_saveexec_b64 s[8:9], vcc
	s_cbranch_execz .LBB0_1407
	v_mov_b32_e32 v2, 0
	global_load_dword v3, v2, s[10:11] sc1
	s_mov_b64 s[16:17], 0
	s_waitcnt vmcnt(0)
	v_cmp_eq_u32_e32 vcc, v3, v4
	s_and_saveexec_b64 s[14:15], vcc
	s_cbranch_execz .LBB0_1406
	s_add_u32 s12, s70, 0x1200
	s_addc_u32 s13, s71, 0
	s_mov_b32 s2, 1
	s_branch .LBB0_1398

	.amdhsa_kernel _Z6mk_fwd4Args
		.amdhsa_group_segment_fixed_size 0
		.amdhsa_private_segment_fixed_size 0
		.amdhsa_kernarg_size 504
		.amdhsa_user_sgpr_count 2
		.amdhsa_user_sgpr_dispatch_ptr 0
		.amdhsa_user_sgpr_queue_ptr 0
		.amdhsa_user_sgpr_kernarg_segment_ptr 1
		.amdhsa_user_sgpr_dispatch_id 0
		.amdhsa_user_sgpr_kernarg_preload_length 0
		.amdhsa_user_sgpr_kernarg_preload_offset 0
		.amdhsa_user_sgpr_private_segment_size 0
		.amdhsa_uses_dynamic_stack 0
		.amdhsa_enable_private_segment 0
		.amdhsa_system_sgpr_workgroup_id_x 1
		.amdhsa_system_sgpr_workgroup_id_y 0
		.amdhsa_system_sgpr_workgroup_id_z 0
		.amdhsa_system_sgpr_workgroup_info 0
		.amdhsa_system_vgpr_workitem_id 0
		.amdhsa_next_free_vgpr 256
		.amdhsa_next_free_sgpr 102
		.amdhsa_accum_offset 256
		.amdhsa_reserve_vcc 1
		.amdhsa_float_round_mode_32 0
		.amdhsa_float_round_mode_16_64 0
		.amdhsa_float_denorm_mode_32 3
		.amdhsa_float_denorm_mode_16_64 3
		.amdhsa_dx10_clamp 1
		.amdhsa_ieee_mode 1
		.amdhsa_fp16_overflow 0
		.amdhsa_tg_split 0
		.amdhsa_exception_fp_ieee_invalid_op 0
		.amdhsa_exception_fp_denorm_src 0
		.amdhsa_exception_fp_ieee_div_zero 0
		.amdhsa_exception_fp_ieee_overflow 0
		.amdhsa_exception_fp_ieee_underflow 0
		.amdhsa_exception_fp_ieee_inexact 0
		.amdhsa_exception_int_div_zero 0
	.end_amdhsa_kernel
